# FFN2 residual epilogue: gate + all 16 residual quads loaded together, one counted wait per quad, in-place convert (epilogue de-serialisation)
# baseline (speedup 1.0000x reference)
.LBB0_1217:
	s_lshl_b32 s16, s16, 8
	s_or_b32 s16, s16, s10
	v_lshl_add_u32 v130, v129, 3, s16
	v_lshlrev_b32_e32 v128, 10, v128
	v_add3_u32 v162, v128, s13, v130
	v_mov_b32_e32 v129, v163
	v_add_u32_e32 v128, 0x4000, v162
	v_lshl_add_u64 v[164:165], v[128:129], 1, s[42:43]
	v_add_u32_e32 v128, 0x8000, v162
	s_lshl_b64 s[16:17], s[48:49], 2
	v_lshl_add_u64 v[158:159], v[128:129], 1, s[42:43]
	v_add_u32_e32 v128, 0xc000, v162
	s_add_u32 s16, s8, s16
	v_lshl_add_u64 v[200:201], v[162:163], 1, s[42:43]
	v_lshl_add_u64 v[156:157], v[128:129], 1, s[42:43]
	s_addc_u32 s17, s9, s17
	v_ashrrev_i32_e32 v131, 31, v130
	v_lshl_add_u64 v[128:129], v[130:131], 2, s[16:17]
	global_load_dwordx4 v[140:143], v[128:129], off
	global_load_dwordx4 v[136:139], v[128:129], off offset:16
	global_load_dwordx4 v[132:135], v[128:129], off offset:512
	s_nop 0
	global_load_dwordx4 v[128:131], v[128:129], off offset:528
	global_load_dwordx4 v[166:169], v[200:201], off
	global_load_dwordx4 v[176:179], v[200:201], off offset:256
	global_load_dwordx4 v[180:183], v[164:165], off
	global_load_dwordx4 v[184:187], v[164:165], off offset:256
	global_load_dwordx4 v[188:191], v[158:159], off
	global_load_dwordx4 v[192:195], v[158:159], off offset:256
	global_load_dwordx4 v[196:199], v[156:157], off
	global_load_dwordx4 v[206:209], v[156:157], off offset:256
	v_add_u32_e32 v170, 0x20000, v162
	v_mov_b32_e32 v171, v163
	v_lshl_add_u64 v[170:171], v[170:171], 1, s[42:43]
	global_load_dwordx4 v[210:213], v[170:171], off
	global_load_dwordx4 v[214:217], v[170:171], off offset:256
	v_add_u32_e32 v170, 0x24000, v162
	v_mov_b32_e32 v171, v163
	v_lshl_add_u64 v[170:171], v[170:171], 1, s[42:43]
	global_load_dwordx4 v[218:221], v[170:171], off
	global_load_dwordx4 v[222:225], v[170:171], off offset:256
	v_add_u32_e32 v170, 0x28000, v162
	v_mov_b32_e32 v171, v163
	v_lshl_add_u64 v[170:171], v[170:171], 1, s[42:43]
	global_load_dwordx4 v[226:229], v[170:171], off
	global_load_dwordx4 v[230:233], v[170:171], off offset:256
	v_add_u32_e32 v170, 0x2c000, v162
	v_mov_b32_e32 v171, v163
	v_lshl_add_u64 v[170:171], v[170:171], 1, s[42:43]
	global_load_dwordx4 v[234:237], v[170:171], off
	global_load_dwordx4 v[238:241], v[170:171], off offset:256
	s_and_b64 vcc, exec, s[36:37]
	s_mov_b64 s[36:37], -1
	s_waitcnt vmcnt(15)
	v_lshlrev_b32_e32 v170, 16, v166
	v_and_b32_e32 v171, 0xffff0000, v166
	v_pk_fma_f32 v[124:125], v[124:125], v[140:141], v[170:171]
	v_cvt_pk_bf16_f32 v166, v124, v125
	v_lshlrev_b32_e32 v170, 16, v167
	v_and_b32_e32 v171, 0xffff0000, v167
	v_pk_fma_f32 v[126:127], v[126:127], v[142:143], v[170:171]
	v_cvt_pk_bf16_f32 v167, v126, v127
	v_lshlrev_b32_e32 v170, 16, v168
	v_and_b32_e32 v171, 0xffff0000, v168
	v_pk_fma_f32 v[120:121], v[120:121], v[136:137], v[170:171]
	v_cvt_pk_bf16_f32 v168, v120, v121
	v_lshlrev_b32_e32 v170, 16, v169
	v_and_b32_e32 v171, 0xffff0000, v169
	v_pk_fma_f32 v[122:123], v[122:123], v[138:139], v[170:171]
	v_cvt_pk_bf16_f32 v169, v122, v123
	global_store_dwordx4 v[200:201], v[166:169], off
	s_waitcnt vmcnt(15)
	v_lshlrev_b32_e32 v170, 16, v176
	v_and_b32_e32 v171, 0xffff0000, v176
	v_pk_fma_f32 v[116:117], v[116:117], v[132:133], v[170:171]
	v_cvt_pk_bf16_f32 v176, v116, v117
	v_lshlrev_b32_e32 v170, 16, v177
	v_and_b32_e32 v171, 0xffff0000, v177
	v_pk_fma_f32 v[118:119], v[118:119], v[134:135], v[170:171]
	v_cvt_pk_bf16_f32 v177, v118, v119
	v_lshlrev_b32_e32 v170, 16, v178
	v_and_b32_e32 v171, 0xffff0000, v178
	v_pk_fma_f32 v[108:109], v[108:109], v[128:129], v[170:171]
	v_cvt_pk_bf16_f32 v178, v108, v109
	v_lshlrev_b32_e32 v170, 16, v179
	v_and_b32_e32 v171, 0xffff0000, v179
	v_pk_fma_f32 v[110:111], v[110:111], v[130:131], v[170:171]
	v_cvt_pk_bf16_f32 v179, v110, v111
	global_store_dwordx4 v[200:201], v[176:179], off offset:256
	s_waitcnt vmcnt(15)
	v_lshlrev_b32_e32 v170, 16, v180
	v_and_b32_e32 v171, 0xffff0000, v180
	v_pk_fma_f32 v[112:113], v[112:113], v[140:141], v[170:171]
	v_cvt_pk_bf16_f32 v180, v112, v113
	v_lshlrev_b32_e32 v170, 16, v181
	v_and_b32_e32 v171, 0xffff0000, v181
	v_pk_fma_f32 v[114:115], v[114:115], v[142:143], v[170:171]
	v_cvt_pk_bf16_f32 v181, v114, v115
	v_lshlrev_b32_e32 v170, 16, v182
	v_and_b32_e32 v171, 0xffff0000, v182
	v_pk_fma_f32 v[104:105], v[104:105], v[136:137], v[170:171]
	v_cvt_pk_bf16_f32 v182, v104, v105
	v_lshlrev_b32_e32 v170, 16, v183
	v_and_b32_e32 v171, 0xffff0000, v183
	v_pk_fma_f32 v[106:107], v[106:107], v[138:139], v[170:171]
	v_cvt_pk_bf16_f32 v183, v106, v107
	global_store_dwordx4 v[164:165], v[180:183], off
	s_waitcnt vmcnt(15)
	v_lshlrev_b32_e32 v170, 16, v184
	v_and_b32_e32 v171, 0xffff0000, v184
	v_pk_fma_f32 v[100:101], v[100:101], v[132:133], v[170:171]
	v_cvt_pk_bf16_f32 v184, v100, v101
	v_lshlrev_b32_e32 v170, 16, v185
	v_and_b32_e32 v171, 0xffff0000, v185
	v_pk_fma_f32 v[102:103], v[102:103], v[134:135], v[170:171]
	v_cvt_pk_bf16_f32 v185, v102, v103
	v_lshlrev_b32_e32 v170, 16, v186
	v_and_b32_e32 v171, 0xffff0000, v186
	v_pk_fma_f32 v[92:93], v[92:93], v[128:129], v[170:171]
	v_cvt_pk_bf16_f32 v186, v92, v93
	v_lshlrev_b32_e32 v170, 16, v187
	v_and_b32_e32 v171, 0xffff0000, v187
	v_pk_fma_f32 v[94:95], v[94:95], v[130:131], v[170:171]
	v_cvt_pk_bf16_f32 v187, v94, v95
	global_store_dwordx4 v[164:165], v[184:187], off offset:256
	s_waitcnt vmcnt(15)
	v_lshlrev_b32_e32 v170, 16, v188
	v_and_b32_e32 v171, 0xffff0000, v188
	v_pk_fma_f32 v[96:97], v[96:97], v[140:141], v[170:171]
	v_cvt_pk_bf16_f32 v188, v96, v97
	v_lshlrev_b32_e32 v170, 16, v189
	v_and_b32_e32 v171, 0xffff0000, v189
	v_pk_fma_f32 v[98:99], v[98:99], v[142:143], v[170:171]
	v_cvt_pk_bf16_f32 v189, v98, v99
	v_lshlrev_b32_e32 v170, 16, v190
	v_and_b32_e32 v171, 0xffff0000, v190
	v_pk_fma_f32 v[88:89], v[88:89], v[136:137], v[170:171]
	v_cvt_pk_bf16_f32 v190, v88, v89
	v_lshlrev_b32_e32 v170, 16, v191
	v_and_b32_e32 v171, 0xffff0000, v191
	v_pk_fma_f32 v[90:91], v[90:91], v[138:139], v[170:171]
	v_cvt_pk_bf16_f32 v191, v90, v91
	global_store_dwordx4 v[158:159], v[188:191], off
	s_waitcnt vmcnt(15)
	v_lshlrev_b32_e32 v170, 16, v192
	v_and_b32_e32 v171, 0xffff0000, v192
	v_pk_fma_f32 v[84:85], v[84:85], v[132:133], v[170:171]
	v_cvt_pk_bf16_f32 v192, v84, v85
	v_lshlrev_b32_e32 v170, 16, v193
	v_and_b32_e32 v171, 0xffff0000, v193
	v_pk_fma_f32 v[86:87], v[86:87], v[134:135], v[170:171]
	v_cvt_pk_bf16_f32 v193, v86, v87
	v_lshlrev_b32_e32 v170, 16, v194
	v_and_b32_e32 v171, 0xffff0000, v194
	v_pk_fma_f32 v[76:77], v[76:77], v[128:129], v[170:171]
	v_cvt_pk_bf16_f32 v194, v76, v77
	v_lshlrev_b32_e32 v170, 16, v195
	v_and_b32_e32 v171, 0xffff0000, v195
	v_pk_fma_f32 v[78:79], v[78:79], v[130:131], v[170:171]
	v_cvt_pk_bf16_f32 v195, v78, v79
	global_store_dwordx4 v[158:159], v[192:195], off offset:256
	s_waitcnt vmcnt(15)
	v_lshlrev_b32_e32 v170, 16, v196
	v_and_b32_e32 v171, 0xffff0000, v196
	v_pk_fma_f32 v[80:81], v[80:81], v[140:141], v[170:171]
	v_cvt_pk_bf16_f32 v196, v80, v81
	v_lshlrev_b32_e32 v170, 16, v197
	v_and_b32_e32 v171, 0xffff0000, v197
	v_pk_fma_f32 v[82:83], v[82:83], v[142:143], v[170:171]
	v_cvt_pk_bf16_f32 v197, v82, v83
	v_lshlrev_b32_e32 v170, 16, v198
	v_and_b32_e32 v171, 0xffff0000, v198
	v_pk_fma_f32 v[72:73], v[72:73], v[136:137], v[170:171]
	v_cvt_pk_bf16_f32 v198, v72, v73
	v_lshlrev_b32_e32 v170, 16, v199
	v_and_b32_e32 v171, 0xffff0000, v199
	v_pk_fma_f32 v[74:75], v[74:75], v[138:139], v[170:171]
	v_cvt_pk_bf16_f32 v199, v74, v75
	global_store_dwordx4 v[156:157], v[196:199], off
	s_waitcnt vmcnt(15)
	v_lshlrev_b32_e32 v170, 16, v206
	v_and_b32_e32 v171, 0xffff0000, v206
	v_pk_fma_f32 v[68:69], v[68:69], v[132:133], v[170:171]
	v_cvt_pk_bf16_f32 v206, v68, v69
	v_lshlrev_b32_e32 v170, 16, v207
	v_and_b32_e32 v171, 0xffff0000, v207
	v_pk_fma_f32 v[70:71], v[70:71], v[134:135], v[170:171]
	v_cvt_pk_bf16_f32 v207, v70, v71
	v_lshlrev_b32_e32 v170, 16, v208
	v_and_b32_e32 v171, 0xffff0000, v208
	v_pk_fma_f32 v[64:65], v[64:65], v[128:129], v[170:171]
	v_cvt_pk_bf16_f32 v208, v64, v65
	v_lshlrev_b32_e32 v170, 16, v209
	v_and_b32_e32 v171, 0xffff0000, v209
	v_pk_fma_f32 v[66:67], v[66:67], v[130:131], v[170:171]
	v_cvt_pk_bf16_f32 v209, v66, v67
	global_store_dwordx4 v[156:157], v[206:209], off offset:256
	s_waitcnt vmcnt(15)
	v_lshlrev_b32_e32 v170, 16, v210
	v_and_b32_e32 v171, 0xffff0000, v210
	v_pk_fma_f32 v[60:61], v[60:61], v[140:141], v[170:171]
	v_cvt_pk_bf16_f32 v210, v60, v61
	v_lshlrev_b32_e32 v170, 16, v211
	v_and_b32_e32 v171, 0xffff0000, v211
	v_pk_fma_f32 v[62:63], v[62:63], v[142:143], v[170:171]
	v_cvt_pk_bf16_f32 v211, v62, v63
	v_lshlrev_b32_e32 v170, 16, v212
	v_and_b32_e32 v171, 0xffff0000, v212
	v_pk_fma_f32 v[56:57], v[56:57], v[136:137], v[170:171]
	v_cvt_pk_bf16_f32 v212, v56, v57
	v_lshlrev_b32_e32 v170, 16, v213
	v_and_b32_e32 v171, 0xffff0000, v213
	v_pk_fma_f32 v[58:59], v[58:59], v[138:139], v[170:171]
	v_cvt_pk_bf16_f32 v213, v58, v59
	v_add_u32_e32 v166, 0x20000, v162
	v_mov_b32_e32 v167, v163
	v_lshl_add_u64 v[166:167], v[166:167], 1, s[42:43]
	global_store_dwordx4 v[166:167], v[210:213], off
	s_waitcnt vmcnt(15)
	v_lshlrev_b32_e32 v170, 16, v214
	v_and_b32_e32 v171, 0xffff0000, v214
	v_pk_fma_f32 v[52:53], v[52:53], v[132:133], v[170:171]
	v_cvt_pk_bf16_f32 v214, v52, v53
	v_lshlrev_b32_e32 v170, 16, v215
	v_and_b32_e32 v171, 0xffff0000, v215
	v_pk_fma_f32 v[54:55], v[54:55], v[134:135], v[170:171]
	v_cvt_pk_bf16_f32 v215, v54, v55
	v_lshlrev_b32_e32 v170, 16, v216
	v_and_b32_e32 v171, 0xffff0000, v216
	v_pk_fma_f32 v[44:45], v[44:45], v[128:129], v[170:171]
	v_cvt_pk_bf16_f32 v216, v44, v45
	v_lshlrev_b32_e32 v170, 16, v217
	v_and_b32_e32 v171, 0xffff0000, v217
	v_pk_fma_f32 v[46:47], v[46:47], v[130:131], v[170:171]
	v_cvt_pk_bf16_f32 v217, v46, v47
	global_store_dwordx4 v[166:167], v[214:217], off offset:256
	s_waitcnt vmcnt(15)
	v_lshlrev_b32_e32 v170, 16, v218
	v_and_b32_e32 v171, 0xffff0000, v218
	v_pk_fma_f32 v[48:49], v[48:49], v[140:141], v[170:171]
	v_cvt_pk_bf16_f32 v218, v48, v49
	v_lshlrev_b32_e32 v170, 16, v219
	v_and_b32_e32 v171, 0xffff0000, v219
	v_pk_fma_f32 v[50:51], v[50:51], v[142:143], v[170:171]
	v_cvt_pk_bf16_f32 v219, v50, v51
	v_lshlrev_b32_e32 v170, 16, v220
	v_and_b32_e32 v171, 0xffff0000, v220
	v_pk_fma_f32 v[40:41], v[40:41], v[136:137], v[170:171]
	v_cvt_pk_bf16_f32 v220, v40, v41
	v_lshlrev_b32_e32 v170, 16, v221
	v_and_b32_e32 v171, 0xffff0000, v221
	v_pk_fma_f32 v[42:43], v[42:43], v[138:139], v[170:171]
	v_cvt_pk_bf16_f32 v221, v42, v43
	v_add_u32_e32 v166, 0x24000, v162
	v_mov_b32_e32 v167, v163
	v_lshl_add_u64 v[166:167], v[166:167], 1, s[42:43]
	global_store_dwordx4 v[166:167], v[218:221], off
	s_waitcnt vmcnt(15)
	v_lshlrev_b32_e32 v170, 16, v222
	v_and_b32_e32 v171, 0xffff0000, v222
	v_pk_fma_f32 v[36:37], v[36:37], v[132:133], v[170:171]
	v_cvt_pk_bf16_f32 v222, v36, v37
	v_lshlrev_b32_e32 v170, 16, v223
	v_and_b32_e32 v171, 0xffff0000, v223
	v_pk_fma_f32 v[38:39], v[38:39], v[134:135], v[170:171]
	v_cvt_pk_bf16_f32 v223, v38, v39
	v_lshlrev_b32_e32 v170, 16, v224
	v_and_b32_e32 v171, 0xffff0000, v224
	v_pk_fma_f32 v[28:29], v[28:29], v[128:129], v[170:171]
	v_cvt_pk_bf16_f32 v224, v28, v29
	v_lshlrev_b32_e32 v170, 16, v225
	v_and_b32_e32 v171, 0xffff0000, v225
	v_pk_fma_f32 v[30:31], v[30:31], v[130:131], v[170:171]
	v_cvt_pk_bf16_f32 v225, v30, v31
	global_store_dwordx4 v[166:167], v[222:225], off offset:256
	s_waitcnt vmcnt(15)
	v_lshlrev_b32_e32 v170, 16, v226
	v_and_b32_e32 v171, 0xffff0000, v226
	v_pk_fma_f32 v[32:33], v[32:33], v[140:141], v[170:171]
	v_cvt_pk_bf16_f32 v226, v32, v33
	v_lshlrev_b32_e32 v170, 16, v227
	v_and_b32_e32 v171, 0xffff0000, v227
	v_pk_fma_f32 v[34:35], v[34:35], v[142:143], v[170:171]
	v_cvt_pk_bf16_f32 v227, v34, v35
	v_lshlrev_b32_e32 v170, 16, v228
	v_and_b32_e32 v171, 0xffff0000, v228
	v_pk_fma_f32 v[24:25], v[24:25], v[136:137], v[170:171]
	v_cvt_pk_bf16_f32 v228, v24, v25
	v_lshlrev_b32_e32 v170, 16, v229
	v_and_b32_e32 v171, 0xffff0000, v229
	v_pk_fma_f32 v[26:27], v[26:27], v[138:139], v[170:171]
	v_cvt_pk_bf16_f32 v229, v26, v27
	v_add_u32_e32 v166, 0x28000, v162
	v_mov_b32_e32 v167, v163
	v_lshl_add_u64 v[166:167], v[166:167], 1, s[42:43]
	global_store_dwordx4 v[166:167], v[226:229], off
	s_waitcnt vmcnt(15)
	v_lshlrev_b32_e32 v170, 16, v230
	v_and_b32_e32 v171, 0xffff0000, v230
	v_pk_fma_f32 v[20:21], v[20:21], v[132:133], v[170:171]
	v_cvt_pk_bf16_f32 v230, v20, v21
	v_lshlrev_b32_e32 v170, 16, v231
	v_and_b32_e32 v171, 0xffff0000, v231
	v_pk_fma_f32 v[22:23], v[22:23], v[134:135], v[170:171]
	v_cvt_pk_bf16_f32 v231, v22, v23
	v_lshlrev_b32_e32 v170, 16, v232
	v_and_b32_e32 v171, 0xffff0000, v232
	v_pk_fma_f32 v[12:13], v[12:13], v[128:129], v[170:171]
	v_cvt_pk_bf16_f32 v232, v12, v13
	v_lshlrev_b32_e32 v170, 16, v233
	v_and_b32_e32 v171, 0xffff0000, v233
	v_pk_fma_f32 v[14:15], v[14:15], v[130:131], v[170:171]
	v_cvt_pk_bf16_f32 v233, v14, v15
	global_store_dwordx4 v[166:167], v[230:233], off offset:256
	s_waitcnt vmcnt(15)
	v_lshlrev_b32_e32 v170, 16, v234
	v_and_b32_e32 v171, 0xffff0000, v234
	v_pk_fma_f32 v[16:17], v[16:17], v[140:141], v[170:171]
	v_cvt_pk_bf16_f32 v234, v16, v17
	v_lshlrev_b32_e32 v170, 16, v235
	v_and_b32_e32 v171, 0xffff0000, v235
	v_pk_fma_f32 v[18:19], v[18:19], v[142:143], v[170:171]
	v_cvt_pk_bf16_f32 v235, v18, v19
	v_lshlrev_b32_e32 v170, 16, v236
	v_and_b32_e32 v171, 0xffff0000, v236
	v_pk_fma_f32 v[8:9], v[8:9], v[136:137], v[170:171]
	v_cvt_pk_bf16_f32 v236, v8, v9
	v_lshlrev_b32_e32 v170, 16, v237
	v_and_b32_e32 v171, 0xffff0000, v237
	v_pk_fma_f32 v[10:11], v[10:11], v[138:139], v[170:171]
	v_cvt_pk_bf16_f32 v237, v10, v11
	v_add_u32_e32 v166, 0x2c000, v162
	v_mov_b32_e32 v167, v163
	v_lshl_add_u64 v[166:167], v[166:167], 1, s[42:43]
	global_store_dwordx4 v[166:167], v[234:237], off
	s_waitcnt vmcnt(15)
	v_lshlrev_b32_e32 v170, 16, v238
	v_and_b32_e32 v171, 0xffff0000, v238
	v_pk_fma_f32 v[4:5], v[4:5], v[132:133], v[170:171]
	v_cvt_pk_bf16_f32 v238, v4, v5
	v_lshlrev_b32_e32 v170, 16, v239
	v_and_b32_e32 v171, 0xffff0000, v239
	v_pk_fma_f32 v[6:7], v[6:7], v[134:135], v[170:171]
	v_cvt_pk_bf16_f32 v239, v6, v7
	v_lshlrev_b32_e32 v170, 16, v240
	v_and_b32_e32 v171, 0xffff0000, v240
	v_pk_fma_f32 v[0:1], v[0:1], v[128:129], v[170:171]
	v_cvt_pk_bf16_f32 v240, v0, v1
	v_lshlrev_b32_e32 v170, 16, v241
	v_and_b32_e32 v171, 0xffff0000, v241
	v_pk_fma_f32 v[2:3], v[2:3], v[130:131], v[170:171]
	v_cvt_pk_bf16_f32 v241, v2, v3
	global_store_dwordx4 v[166:167], v[238:241], off offset:256
	s_cbranch_vccnz .LBB0_1202
	s_andn2_b64 vcc, exec, s[0:1]
	s_cbranch_vccnz .LBB0_1201
	s_barrier
	s_branch .LBB0_1201
